# ATTN compressed-branch passes: bias-table addresses from one per-block base plus a per-entry constant (2 VALU per entry instead of 4)
# baseline (speedup 1.0000x reference)
.LBB0_1285:
	s_mul_i32 s2, s3, 0x2400
	v_add_u32_e32 v33, s2, v156
	v_add_u32_e32 v42, v33, v157
	ds_read_b128 v[34:37], v42
	ds_read_b128 v[38:41], v42 offset:32
	v_add_u32_e32 v33, v33, v158
	v_mov_b32_e32 v68, v48
	s_lshl_b32 s3, s3, 6
	v_subrev_u32_e32 v255, s3, v159
	v_lshl_add_u32 v255, v255, 6, v252
	s_waitcnt lgkmcnt(1)
	v_mfma_f32_32x32x16_bf16 v[50:65], v[34:37], v[80:83], 0
	ds_read_b128 v[34:37], v42 offset:64
	s_waitcnt lgkmcnt(1)
	v_mfma_f32_32x32x16_bf16 v[50:65], v[38:41], v[84:87], v[50:65]
	s_waitcnt lgkmcnt(0)
	v_mfma_f32_32x32x16_bf16 v[50:65], v[34:37], v[88:91], v[50:65]
	ds_read_b128 v[34:37], v42 offset:96
	s_waitcnt lgkmcnt(0)
	v_mfma_f32_32x32x16_bf16 v[50:65], v[34:37], v[92:95], v[50:65]
	ds_read_b128 v[34:37], v33
	ds_read_b128 v[70:73], v33 offset:32
	s_waitcnt lgkmcnt(1)
	v_mfma_f32_32x32x16_bf16 v[34:49], v[34:37], v[80:83], 0
	s_waitcnt lgkmcnt(0)
	v_mfma_f32_32x32x16_bf16 v[34:49], v[70:73], v[84:87], v[34:49]
	ds_read_b128 v[70:73], v33 offset:64
	s_waitcnt lgkmcnt(0)
	v_mfma_f32_32x32x16_bf16 v[34:49], v[70:73], v[88:91], v[34:49]
	ds_read_b128 v[70:73], v33 offset:96
	v_mov_b32_e32 v33, v255
	v_med3_i32 v33, v33, s101, v253
	ds_read_b32 v69, v33 offset:256
	v_add_u32_e32 v33, 0xffffffc0, v255
	v_med3_i32 v33, v33, s101, v253
	s_waitcnt lgkmcnt(1)
	v_mfma_f32_32x32x16_bf16 v[34:49], v[70:73], v[92:95], v[34:49]
	ds_read_b32 v70, v33 offset:256
	v_add_u32_e32 v33, 0xffffff80, v255
	v_med3_i32 v33, v33, s101, v253
	ds_read_b32 v71, v33 offset:256
	v_add_u32_e32 v33, 0xffffff40, v255
	v_med3_i32 v33, v33, s101, v253
	ds_read_b32 v72, v33 offset:256
	v_add_u32_e32 v33, 0xfffffe00, v255
	v_med3_i32 v33, v33, s101, v253
	ds_read_b32 v75, v33 offset:256
	v_add_u32_e32 v33, 0xfffffdc0, v255
	v_med3_i32 v33, v33, s101, v253
	ds_read_b32 v73, v33 offset:256
	v_add_u32_e32 v33, 0xfffffd80, v255
	v_med3_i32 v33, v33, s101, v253
	ds_read_b32 v74, v33 offset:256
	v_add_u32_e32 v33, 0xfffffd40, v255
	v_med3_i32 v33, v33, s101, v253
	ds_read_b32 v76, v33 offset:256
	s_waitcnt lgkmcnt(7)
	v_fmac_f32_e32 v69, 0x3fb8aa3b, v50
	s_waitcnt lgkmcnt(6)
	v_fmac_f32_e32 v70, 0x3fb8aa3b, v51
	v_max3_f32 v33, v69, s70, v70
	s_waitcnt lgkmcnt(5)
	v_fmac_f32_e32 v71, 0x3fb8aa3b, v52
	s_waitcnt lgkmcnt(4)
	v_fmac_f32_e32 v72, 0x3fb8aa3b, v53
	v_max3_f32 v33, v33, v71, v72
	s_waitcnt lgkmcnt(3)
	v_fmac_f32_e32 v75, 0x3fb8aa3b, v54
	s_waitcnt lgkmcnt(2)
	v_fmac_f32_e32 v73, 0x3fb8aa3b, v55
	v_max3_f32 v33, v33, v75, v73
	s_waitcnt lgkmcnt(1)
	v_fmac_f32_e32 v74, 0x3fb8aa3b, v56
	s_waitcnt lgkmcnt(0)
	v_fmac_f32_e32 v76, 0x3fb8aa3b, v57
	v_max3_f32 v33, v33, v74, v76
	v_add_u32_e32 v50, 0xfffffc00, v255
	v_add_u32_e32 v51, 0xfffffbc0, v255
	v_add_u32_e32 v53, 0xfffffb40, v255
	v_add_u32_e32 v55, 0xfffff9c0, v255
	v_med3_i32 v50, v50, s101, v253
	v_med3_i32 v51, v51, s101, v253
	v_add_u32_e32 v52, 0xfffffb80, v255
	v_med3_i32 v53, v53, s101, v253
	v_add_u32_e32 v54, 0xfffffa00, v255
	v_med3_i32 v55, v55, s101, v253
	v_add_u32_e32 v56, 0xfffff980, v255
	v_add_u32_e32 v57, 0xfffff940, v255
	v_med3_i32 v52, v52, s101, v253
	v_med3_i32 v54, v54, s101, v253
	v_med3_i32 v56, v56, s101, v253
	v_med3_i32 v57, v57, s101, v253
	v_mov_b32_e32 v97, v57
	ds_read_b32 v96, v50 offset:256
	ds_read_b32 v79, v51 offset:256
	ds_read_b32 v78, v52 offset:256
	ds_read_b32 v77, v53 offset:256
	ds_read_b32 v57, v54 offset:256
	ds_read_b32 v55, v55 offset:256
	ds_read_b32 v53, v56 offset:256
	ds_read_b32 v51, v97 offset:256
	s_waitcnt lgkmcnt(7)
	v_fmac_f32_e32 v96, 0x3fb8aa3b, v58
	s_waitcnt lgkmcnt(6)
	v_fmac_f32_e32 v79, 0x3fb8aa3b, v59
	v_max3_f32 v33, v33, v96, v79
	s_waitcnt lgkmcnt(5)
	v_fmac_f32_e32 v78, 0x3fb8aa3b, v60
	s_waitcnt lgkmcnt(4)
	v_fmac_f32_e32 v77, 0x3fb8aa3b, v61
	v_max3_f32 v33, v33, v78, v77
	s_waitcnt lgkmcnt(3)
	v_fmac_f32_e32 v57, 0x3fb8aa3b, v62
	s_waitcnt lgkmcnt(2)
	v_fmac_f32_e32 v55, 0x3fb8aa3b, v63
	v_max3_f32 v33, v33, v57, v55
	s_waitcnt lgkmcnt(1)
	v_fmac_f32_e32 v53, 0x3fb8aa3b, v64
	s_waitcnt lgkmcnt(0)
	v_fmac_f32_e32 v51, 0x3fb8aa3b, v65
	v_max3_f32 v33, v33, v53, v51
	v_add_u32_e32 v58, 0xfffff600, v255
	v_med3_i32 v58, v58, s101, v253
	v_mov_b32_e32 v61, v58
	v_add_u32_e32 v58, 0xfffff5c0, v255
	v_med3_i32 v58, v58, s101, v253
	v_mov_b32_e32 v63, v58
	v_add_u32_e32 v58, 0xfffff580, v255
	v_med3_i32 v58, v58, s101, v253
	v_add_u32_e32 v50, 0xfffff800, v255
	v_add_u32_e32 v52, 0xfffff7c0, v255
	v_add_u32_e32 v54, 0xfffff780, v255
	v_add_u32_e32 v56, 0xfffff740, v255
	v_mov_b32_e32 v64, v58
	v_med3_i32 v50, v50, s101, v253
	v_med3_i32 v52, v52, s101, v253
	v_med3_i32 v54, v54, s101, v253
	v_med3_i32 v56, v56, s101, v253
	v_add_u32_e32 v58, 0xfffff540, v255
	v_med3_i32 v58, v58, s101, v253
	v_mov_b32_e32 v65, v58
	ds_read_b32 v62, v50 offset:256
	ds_read_b32 v60, v52 offset:256
	ds_read_b32 v59, v54 offset:256
	ds_read_b32 v58, v56 offset:256
	ds_read_b32 v56, v61 offset:256
	ds_read_b32 v54, v63 offset:256
	ds_read_b32 v52, v64 offset:256
	ds_read_b32 v50, v65 offset:256
	s_waitcnt lgkmcnt(7)
	v_fmac_f32_e32 v62, 0x3fb8aa3b, v34
	s_waitcnt lgkmcnt(6)
	v_fmac_f32_e32 v60, 0x3fb8aa3b, v35
	v_max3_f32 v33, v33, v62, v60
	s_waitcnt lgkmcnt(5)
	v_fmac_f32_e32 v59, 0x3fb8aa3b, v36
	s_waitcnt lgkmcnt(4)
	v_fmac_f32_e32 v58, 0x3fb8aa3b, v37
	v_max3_f32 v33, v33, v59, v58
	s_waitcnt lgkmcnt(3)
	v_fmac_f32_e32 v56, 0x3fb8aa3b, v38
	s_waitcnt lgkmcnt(2)
	v_fmac_f32_e32 v54, 0x3fb8aa3b, v39
	v_max3_f32 v33, v33, v56, v54
	s_waitcnt lgkmcnt(1)
	v_fmac_f32_e32 v52, 0x3fb8aa3b, v40
	s_waitcnt lgkmcnt(0)
	v_fmac_f32_e32 v50, 0x3fb8aa3b, v41
	v_max3_f32 v33, v33, v52, v50
	v_add_u32_e32 v39, 0xfffff1c0, v255
	v_med3_i32 v39, v39, s101, v253
	v_mov_b32_e32 v63, v39
	v_add_u32_e32 v39, 0xfffff180, v255
	v_med3_i32 v39, v39, s101, v253
	v_add_u32_e32 v34, 0xfffff400, v255
	v_add_u32_e32 v35, 0xfffff3c0, v255
	v_add_u32_e32 v36, 0xfffff380, v255
	v_add_u32_e32 v37, 0xfffff340, v255
	v_add_u32_e32 v38, 0xfffff200, v255
	v_mov_b32_e32 v64, v39
	v_med3_i32 v34, v34, s101, v253
	v_med3_i32 v35, v35, s101, v253
	v_med3_i32 v36, v36, s101, v253
	v_med3_i32 v37, v37, s101, v253
	v_med3_i32 v38, v38, s101, v253
	v_add_u32_e32 v39, 0xfffff140, v255
	v_med3_i32 v39, v39, s101, v253
	v_mov_b32_e32 v65, v39
	ds_read_b32 v61, v34 offset:256
	ds_read_b32 v41, v35 offset:256
	ds_read_b32 v40, v36 offset:256
	ds_read_b32 v39, v37 offset:256
	ds_read_b32 v38, v38 offset:256
	ds_read_b32 v37, v63 offset:256
	ds_read_b32 v36, v64 offset:256
	ds_read_b32 v35, v65 offset:256
	s_waitcnt lgkmcnt(7)
	v_fmac_f32_e32 v61, 0x3fb8aa3b, v42
	s_waitcnt lgkmcnt(6)
	v_fmac_f32_e32 v41, 0x3fb8aa3b, v43
	v_max3_f32 v33, v33, v61, v41
	s_waitcnt lgkmcnt(5)
	v_fmac_f32_e32 v40, 0x3fb8aa3b, v44
	s_waitcnt lgkmcnt(4)
	v_fmac_f32_e32 v39, 0x3fb8aa3b, v45
	v_max3_f32 v33, v33, v40, v39
	s_waitcnt lgkmcnt(3)
	v_fmac_f32_e32 v38, 0x3fb8aa3b, v46
	s_waitcnt lgkmcnt(2)
	v_fmac_f32_e32 v37, 0x3fb8aa3b, v47
	v_max3_f32 v33, v33, v38, v37
	s_waitcnt lgkmcnt(1)
	v_fmac_f32_e32 v36, 0x3fb8aa3b, v48
	s_waitcnt lgkmcnt(0)
	v_fmac_f32_e32 v35, 0x3fb8aa3b, v49
	v_max3_f32 v33, v33, v36, v35
	ds_bpermute_b32 v34, v155, v33
	s_waitcnt lgkmcnt(0)
	v_max3_f32 v48, v68, v33, v34
	v_cmp_neq_f32_e32 vcc, s70, v48
	s_nop 1
	v_cndmask_b32_e32 v33, 0, v48, vcc
	v_sub_f32_e32 v34, v68, v33
	v_exp_f32_e32 v34, v34
	s_nop 0
	v_cmp_neq_f32_e32 vcc, 1.0, v34
	s_cbranch_vccz .LBB0_1287
	v_mul_f32_e32 v30, v30, v34
	v_mul_f32_e32 v31, v31, v34
	v_mul_f32_e32 v28, v28, v34
	v_mul_f32_e32 v29, v29, v34
	v_mul_f32_e32 v26, v26, v34
	v_mul_f32_e32 v27, v27, v34
	v_mul_f32_e32 v24, v24, v34
	v_mul_f32_e32 v25, v25, v34
	v_mul_f32_e32 v22, v22, v34
	v_mul_f32_e32 v23, v23, v34
	v_mul_f32_e32 v20, v20, v34
	v_mul_f32_e32 v21, v21, v34
	v_mul_f32_e32 v18, v18, v34
	v_mul_f32_e32 v19, v19, v34
	v_mul_f32_e32 v16, v16, v34
	v_mul_f32_e32 v17, v17, v34
	v_mul_f32_e32 v14, v14, v34
	v_mul_f32_e32 v15, v15, v34
	v_mul_f32_e32 v12, v12, v34
	v_mul_f32_e32 v13, v13, v34
	v_mul_f32_e32 v10, v10, v34
	v_mul_f32_e32 v11, v11, v34
	v_mul_f32_e32 v8, v8, v34
	v_mul_f32_e32 v9, v9, v34
	v_mul_f32_e32 v6, v6, v34
	v_mul_f32_e32 v7, v7, v34
	v_mul_f32_e32 v4, v4, v34
	v_mul_f32_e32 v5, v5, v34
	v_mul_f32_e32 v2, v2, v34
	v_mul_f32_e32 v3, v3, v34
	v_mul_f32_e32 v0, v0, v34
	v_mul_f32_e32 v1, v1, v34

.LBB0_1291:
	s_mul_i32 s3, s2, 0x2400
	v_add_u32_e32 v8, s3, v156
	v_add_u32_e32 v9, v8, v157
	ds_read_b128 v[0:3], v9
	ds_read_b128 v[4:7], v9 offset:32
	s_lshl_b32 s2, s2, 6
	v_subrev_u32_e32 v255, s2, v159
	v_lshl_add_u32 v255, v255, 6, v252
	s_waitcnt lgkmcnt(1)
	v_mfma_f32_32x32x16_bf16 v[16:31], v[0:3], v[80:83], 0
	ds_read_b128 v[0:3], v9 offset:64
	v_add_u32_e32 v8, v8, v158
	v_mov_b32_e32 v10, v255
	v_add_u32_e32 v11, 0xffffffc0, v255
	v_add_u32_e32 v12, 0xffffff80, v255
	s_waitcnt lgkmcnt(1)
	v_mfma_f32_32x32x16_bf16 v[16:31], v[4:7], v[84:87], v[16:31]
	ds_read_b128 v[4:7], v9 offset:96
	v_add_u32_e32 v9, 0xffffff40, v255
	v_add_u32_e32 v48, 0xfffffe00, v255
	v_add_u32_e32 v53, 0xfffffdc0, v255
	s_waitcnt lgkmcnt(1)
	v_mfma_f32_32x32x16_bf16 v[16:31], v[0:3], v[88:91], v[16:31]
	ds_read_b128 v[0:3], v8
	ds_read_b128 v[36:39], v8 offset:32
	ds_read_b128 v[40:43], v8 offset:64
	ds_read_b128 v[44:47], v8 offset:96
	v_med3_i32 v8, v10, s101, v253
	v_mov_b32_e32 v49, v8
	v_med3_i32 v48, v48, s101, v253
	v_med3_i32 v53, v53, s101, v253
	s_waitcnt lgkmcnt(4)
	v_mfma_f32_32x32x16_bf16 v[16:31], v[4:7], v[92:95], v[16:31]
	v_med3_i32 v4, v11, s101, v253
	v_med3_i32 v5, v12, s101, v253
	v_med3_i32 v6, v9, s101, v253
	v_mov_b32_e32 v50, v4
	v_mov_b32_e32 v51, v5
	v_mov_b32_e32 v52, v6
	s_waitcnt lgkmcnt(3)
	v_mfma_f32_32x32x16_bf16 v[0:15], v[0:3], v[80:83], 0
	s_waitcnt lgkmcnt(2)
	v_mfma_f32_32x32x16_bf16 v[0:15], v[36:39], v[84:87], v[0:15]
	v_add_u32_e32 v36, 0xfffffd80, v255
	v_add_u32_e32 v37, 0xfffffd40, v255
	v_med3_i32 v36, v36, s101, v253
	v_med3_i32 v37, v37, s101, v253
	s_waitcnt lgkmcnt(1)
	v_mfma_f32_32x32x16_bf16 v[0:15], v[40:43], v[88:91], v[0:15]
	ds_read_b32 v38, v49 offset:256
	ds_read_b32 v39, v50 offset:256
	ds_read_b32 v40, v51 offset:256
	ds_read_b32 v41, v52 offset:256
	ds_read_b32 v42, v48 offset:256
	ds_read_b32 v43, v53 offset:256
	ds_read_b32 v36, v36 offset:256
	ds_read_b32 v37, v37 offset:256
	s_waitcnt lgkmcnt(8)
	v_mfma_f32_32x32x16_bf16 v[0:15], v[44:47], v[92:95], v[0:15]
	s_waitcnt lgkmcnt(7)
	v_fmac_f32_e32 v38, 0x3fb8aa3b, v16
	s_waitcnt lgkmcnt(6)
	v_fmac_f32_e32 v39, 0x3fb8aa3b, v17
	s_waitcnt lgkmcnt(5)
	v_fmac_f32_e32 v40, 0x3fb8aa3b, v18
	s_waitcnt lgkmcnt(4)
	v_fmac_f32_e32 v41, 0x3fb8aa3b, v19
	s_waitcnt lgkmcnt(3)
	v_fmac_f32_e32 v42, 0x3fb8aa3b, v20
	s_waitcnt lgkmcnt(2)
	v_fmac_f32_e32 v43, 0x3fb8aa3b, v21
	s_waitcnt lgkmcnt(1)
	v_fmac_f32_e32 v36, 0x3fb8aa3b, v22
	s_waitcnt lgkmcnt(0)
	v_fmac_f32_e32 v37, 0x3fb8aa3b, v23
	v_add_u32_e32 v16, 0xfffffc00, v255
	v_add_u32_e32 v17, 0xfffffbc0, v255
	v_add_u32_e32 v18, 0xfffffb80, v255
	v_add_u32_e32 v19, 0xfffffb40, v255
	v_add_u32_e32 v20, 0xfffffa00, v255
	v_add_u32_e32 v21, 0xfffff9c0, v255
	v_add_u32_e32 v22, 0xfffff980, v255
	v_add_u32_e32 v23, 0xfffff940, v255
	v_med3_i32 v16, v16, s101, v253
	v_med3_i32 v17, v17, s101, v253
	v_med3_i32 v18, v18, s101, v253
	v_med3_i32 v19, v19, s101, v253
	v_med3_i32 v20, v20, s101, v253
	v_med3_i32 v21, v21, s101, v253
	v_med3_i32 v22, v22, s101, v253
	v_med3_i32 v23, v23, s101, v253
	ds_read_b32 v16, v16 offset:256
	ds_read_b32 v17, v17 offset:256
	ds_read_b32 v18, v18 offset:256
	ds_read_b32 v19, v19 offset:256
	ds_read_b32 v20, v20 offset:256
	ds_read_b32 v21, v21 offset:256
	ds_read_b32 v22, v22 offset:256
	ds_read_b32 v23, v23 offset:256
	s_waitcnt lgkmcnt(7)
	v_fmac_f32_e32 v16, 0x3fb8aa3b, v24
	s_waitcnt lgkmcnt(6)
	v_fmac_f32_e32 v17, 0x3fb8aa3b, v25
	s_waitcnt lgkmcnt(5)
	v_fmac_f32_e32 v18, 0x3fb8aa3b, v26
	s_waitcnt lgkmcnt(4)
	v_fmac_f32_e32 v19, 0x3fb8aa3b, v27
	s_waitcnt lgkmcnt(3)
	v_fmac_f32_e32 v20, 0x3fb8aa3b, v28
	s_waitcnt lgkmcnt(2)
	v_fmac_f32_e32 v21, 0x3fb8aa3b, v29
	s_waitcnt lgkmcnt(1)
	v_fmac_f32_e32 v22, 0x3fb8aa3b, v30
	s_waitcnt lgkmcnt(0)
	v_fmac_f32_e32 v23, 0x3fb8aa3b, v31
	v_add_u32_e32 v24, 0xfffff800, v255
	v_add_u32_e32 v25, 0xfffff7c0, v255
	v_add_u32_e32 v26, 0xfffff780, v255
	v_add_u32_e32 v27, 0xfffff740, v255
	v_add_u32_e32 v28, 0xfffff600, v255
	v_add_u32_e32 v29, 0xfffff5c0, v255
	v_add_u32_e32 v30, 0xfffff580, v255
	v_add_u32_e32 v31, 0xfffff540, v255
	v_med3_i32 v24, v24, s101, v253
	v_med3_i32 v25, v25, s101, v253
	v_med3_i32 v26, v26, s101, v253
	v_med3_i32 v27, v27, s101, v253
	v_med3_i32 v28, v28, s101, v253
	v_med3_i32 v29, v29, s101, v253
	v_med3_i32 v30, v30, s101, v253
	v_med3_i32 v31, v31, s101, v253
	ds_read_b32 v24, v24 offset:256
	ds_read_b32 v25, v25 offset:256
	ds_read_b32 v26, v26 offset:256
	ds_read_b32 v27, v27 offset:256
	ds_read_b32 v28, v28 offset:256
	ds_read_b32 v29, v29 offset:256
	ds_read_b32 v30, v30 offset:256
	ds_read_b32 v31, v31 offset:256
	s_waitcnt lgkmcnt(7)
	v_fmac_f32_e32 v24, 0x3fb8aa3b, v0
	s_waitcnt lgkmcnt(6)
	v_fmac_f32_e32 v25, 0x3fb8aa3b, v1
	s_waitcnt lgkmcnt(5)
	v_fmac_f32_e32 v26, 0x3fb8aa3b, v2
	s_waitcnt lgkmcnt(4)
	v_fmac_f32_e32 v27, 0x3fb8aa3b, v3
	s_waitcnt lgkmcnt(3)
	v_fmac_f32_e32 v28, 0x3fb8aa3b, v4
	s_waitcnt lgkmcnt(2)
	v_fmac_f32_e32 v29, 0x3fb8aa3b, v5
	s_waitcnt lgkmcnt(1)
	v_fmac_f32_e32 v30, 0x3fb8aa3b, v6
	s_waitcnt lgkmcnt(0)
	v_fmac_f32_e32 v31, 0x3fb8aa3b, v7
	v_add_u32_e32 v0, 0xfffff400, v255
	v_add_u32_e32 v1, 0xfffff3c0, v255
	v_add_u32_e32 v2, 0xfffff380, v255
	v_add_u32_e32 v3, 0xfffff340, v255
	v_add_u32_e32 v4, 0xfffff200, v255
	v_add_u32_e32 v5, 0xfffff1c0, v255
	v_add_u32_e32 v6, 0xfffff180, v255
	v_add_u32_e32 v7, 0xfffff140, v255
	v_med3_i32 v0, v0, s101, v253
	v_med3_i32 v1, v1, s101, v253
	v_med3_i32 v2, v2, s101, v253
	v_med3_i32 v3, v3, s101, v253
	v_med3_i32 v4, v4, s101, v253
	v_med3_i32 v5, v5, s101, v253
	v_med3_i32 v6, v6, s101, v253
	v_med3_i32 v7, v7, s101, v253
	ds_read_b32 v0, v0 offset:256
	ds_read_b32 v1, v1 offset:256
	ds_read_b32 v2, v2 offset:256
	ds_read_b32 v3, v3 offset:256
	ds_read_b32 v4, v4 offset:256
	ds_read_b32 v5, v5 offset:256
	ds_read_b32 v6, v6 offset:256
	ds_read_b32 v7, v7 offset:256
	s_waitcnt lgkmcnt(7)
	v_fmac_f32_e32 v0, 0x3fb8aa3b, v8
	s_waitcnt lgkmcnt(6)
	v_fmac_f32_e32 v1, 0x3fb8aa3b, v9
	s_waitcnt lgkmcnt(5)
	v_fmac_f32_e32 v2, 0x3fb8aa3b, v10
	s_waitcnt lgkmcnt(4)
	v_fmac_f32_e32 v3, 0x3fb8aa3b, v11
	s_waitcnt lgkmcnt(3)
	v_fmac_f32_e32 v4, 0x3fb8aa3b, v12
	s_waitcnt lgkmcnt(2)
	v_fmac_f32_e32 v5, 0x3fb8aa3b, v13
	s_waitcnt lgkmcnt(1)
	v_fmac_f32_e32 v6, 0x3fb8aa3b, v14
	s_waitcnt lgkmcnt(0)
	v_fmac_f32_e32 v7, 0x3fb8aa3b, v15
	v_sub_f32_e32 v12, v41, v33
	v_exp_f32_e32 v12, v12
	v_sub_f32_e32 v10, v39, v33
	v_sub_f32_e32 v15, v36, v33
	v_sub_f32_e32 v36, v37, v33
	v_sub_f32_e32 v9, v38, v33
	v_sub_f32_e32 v14, v43, v33
	v_sub_f32_e32 v17, v17, v33
	v_sub_f32_e32 v19, v19, v33
	v_sub_f32_e32 v23, v23, v33
	v_sub_f32_e32 v27, v27, v33
	v_sub_f32_e32 v31, v31, v33
	v_sub_f32_e32 v1, v1, v33
	v_sub_f32_e32 v3, v3, v33
	v_exp_f32_e32 v10, v10
	v_exp_f32_e32 v36, v36
	v_sub_f32_e32 v11, v40, v33
	v_sub_f32_e32 v13, v42, v33
	v_sub_f32_e32 v16, v16, v33
	v_sub_f32_e32 v18, v18, v33
	v_sub_f32_e32 v0, v0, v33
	v_sub_f32_e32 v2, v2, v33
	v_sub_f32_e32 v7, v7, v33
	v_exp_f32_e32 v9, v9
	v_exp_f32_e32 v14, v14
	v_exp_f32_e32 v17, v17
	v_exp_f32_e32 v19, v19
	v_exp_f32_e32 v23, v23
	v_exp_f32_e32 v27, v27
	v_exp_f32_e32 v31, v31
	v_exp_f32_e32 v1, v1
	v_exp_f32_e32 v3, v3
	v_mul_f32_e32 v12, v34, v12
	v_exp_f32_e32 v11, v11
	v_exp_f32_e32 v13, v13
	v_exp_f32_e32 v15, v15
	v_exp_f32_e32 v16, v16
	v_exp_f32_e32 v18, v18
	v_exp_f32_e32 v0, v0
	v_exp_f32_e32 v2, v2
	v_exp_f32_e32 v7, v7
	ds_bpermute_b32 v37, v155, v12
	v_sub_f32_e32 v21, v21, v33
	v_sub_f32_e32 v25, v25, v33
	v_sub_f32_e32 v29, v29, v33
	v_sub_f32_e32 v5, v5, v33
	v_mul_f32_e32 v10, v34, v10
	v_mul_f32_e32 v36, v34, v36
	v_sub_f32_e32 v20, v20, v33
	v_sub_f32_e32 v22, v22, v33
	v_sub_f32_e32 v24, v24, v33
	v_sub_f32_e32 v26, v26, v33
	v_sub_f32_e32 v28, v28, v33
	v_sub_f32_e32 v30, v30, v33
	v_sub_f32_e32 v4, v4, v33
	v_exp_f32_e32 v21, v21
	v_exp_f32_e32 v25, v25
	v_exp_f32_e32 v29, v29
	v_exp_f32_e32 v5, v5
	v_mul_f32_e32 v14, v34, v14
	v_mul_f32_e32 v17, v34, v17
	v_mul_f32_e32 v19, v34, v19
	v_mul_f32_e32 v23, v34, v23
	v_mul_f32_e32 v27, v34, v27
	v_mul_f32_e32 v31, v34, v31
	v_mul_f32_e32 v1, v34, v1
	v_mul_f32_e32 v3, v34, v3
	v_fmac_f32_e32 v10, v34, v9
	ds_bpermute_b32 v9, v155, v36
	v_sub_f32_e32 v6, v6, v33
	v_exp_f32_e32 v20, v20
	v_exp_f32_e32 v22, v22
	v_exp_f32_e32 v24, v24
	v_exp_f32_e32 v26, v26
	v_exp_f32_e32 v28, v28
	v_exp_f32_e32 v30, v30
	v_exp_f32_e32 v4, v4
	v_mul_f32_e32 v7, v34, v7
	v_fmac_f32_e32 v12, v34, v11
	v_fmac_f32_e32 v14, v34, v13
	v_fmac_f32_e32 v36, v34, v15
	ds_bpermute_b32 v11, v155, v19
	v_fmac_f32_e32 v17, v34, v16
	v_fmac_f32_e32 v19, v34, v18
	ds_bpermute_b32 v13, v155, v23
	ds_bpermute_b32 v15, v155, v27
	ds_bpermute_b32 v16, v155, v31
	ds_bpermute_b32 v18, v155, v3
	v_fmac_f32_e32 v1, v34, v0
	v_fmac_f32_e32 v3, v34, v2
	v_exp_f32_e32 v6, v6
	v_add_f32_e32 v1, v1, v3
	s_waitcnt lgkmcnt(6)
	v_cndmask_b32_e64 v3, v37, v35, s[4:5]
	ds_bpermute_b32 v35, v155, v7
	v_mul_f32_e32 v21, v34, v21
	v_mul_f32_e32 v25, v34, v25
	v_mul_f32_e32 v29, v34, v29
	v_mul_f32_e32 v5, v34, v5
	v_add_u32_e32 v8, s2, v110
	v_fmac_f32_e32 v21, v34, v20
	v_fmac_f32_e32 v23, v34, v22
	v_fmac_f32_e32 v25, v34, v24
	v_fmac_f32_e32 v27, v34, v26
	v_fmac_f32_e32 v29, v34, v28
	v_fmac_f32_e32 v31, v34, v30
	v_fmac_f32_e32 v5, v34, v4
	v_add_f32_e32 v0, v10, v12
	v_add_f32_e32 v2, v14, v36
	v_add_f32_e32 v4, v17, v19
	s_waitcnt lgkmcnt(6)
	v_cndmask_b32_e64 v17, v9, v37, s[4:5]
	v_add_u32_e32 v8, 0x9000, v8
	v_add_f32_e32 v10, v21, v23
	v_add_f32_e32 v12, v25, v27
	v_add_f32_e32 v14, v29, v31
	s_waitcnt lgkmcnt(5)
	v_cndmask_b32_e64 v9, v11, v9, s[4:5]
	s_waitcnt lgkmcnt(4)
	v_cndmask_b32_e64 v11, v13, v11, s[4:5]
	s_waitcnt lgkmcnt(3)
	v_cndmask_b32_e64 v13, v15, v13, s[4:5]
	s_waitcnt lgkmcnt(2)
	v_cndmask_b32_e64 v15, v16, v15, s[4:5]
	v_fmac_f32_e32 v7, v34, v6
	v_add_f32_e32 v0, v0, v3
	v_add_f32_e32 v2, v2, v17
	s_waitcnt lgkmcnt(1)
	v_cndmask_b32_e64 v16, v18, v16, s[4:5]
	v_add_f32_e32 v3, v4, v9
	v_add_f32_e32 v4, v10, v11
	v_add_f32_e32 v6, v12, v13
	v_add_f32_e32 v9, v14, v15
	v_add_f32_e32 v5, v5, v7
	ds_write2_b32 v8, v0, v2 offset1:2
	ds_write2_b32 v8, v3, v4 offset0:4 offset1:6
	ds_write2_b32 v8, v6, v9 offset0:8 offset1:10
	s_waitcnt lgkmcnt(3)
	v_cndmask_b32_e64 v0, v35, v18, s[4:5]
	s_mov_b32 s2, 1
	s_and_b64 vcc, exec, s[30:31]
	s_mov_b64 s[30:31], 0
	v_add_f32_e32 v1, v1, v16
	v_add_f32_e32 v0, v5, v0
	ds_write2_b32 v8, v1, v0 offset0:12 offset1:14
	s_cbranch_vccnz .LBB0_1291
